# v95 plus a short P9 entry skew (1 x s_sleep 127) for two of the four workgroups that share the same hid rows, so the leading pair brings the rows into L2 for the trailing pair
# baseline (speedup 1.0000x reference)
.LBB0_564:
	s_or_b64 exec, exec, s[6:7]
	s_bitcmp1_b32 s2, 6
	s_cbranch_scc0 .Lst9_skip
	s_movk_i32 s74, 1

.Lst9_skip:
	v_mov_b32_e32 v0, v254
	s_barrier
	s_and_b64 vcc, exec, s[4:5]
	v_readfirstlane_b32 s8, v254
	s_cbranch_vccnz .LBB0_588
	s_lshr_b32 s0, s3, 29
	s_add_i32 s5, s2, s0
	s_and_b32 s0, s5, -8
	s_sub_i32 s6, s2, s0
	s_cmp_gt_i32 s6, -1
	s_cbranch_scc0 .LBB0_567
	s_lshl_b32 s4, s6, 6
	s_ashr_i32 s5, s5, 3
	s_cbranch_execz .LBB0_568
	s_branch .LBB0_569
